# redundant wait+barrier at the entry of P3/P4/P5/P8 (directly behind the grid barrier's closing barrier) removed
# baseline (speedup 1.0000x reference)
; __global__ void __launch_bounds__(NTHR, 2) mega(Args args) {
;     ...
;     if (IN(3)) { for (int rep = 0; rep < (MK_DUP == 3 ? 2 : 1); ++rep) {
;         __syncthreads();
;         const bf16* DQb = (const bf16*)(ws + WS_DQ); const bf16* DKb = (const bf16*)(ws + WS_DK); const bf16* DVb = (const bf16*)(ws + WS_DV); bf16* ODb = (bf16*)(ws + WS_OD);
;         for (int idx = blockIdx.x; idx < 512; idx += G) {
;             const int b = idx & 7, rest = idx >> 3, hp = rest >> 3, qb = rest & 7;
;             att::attn_unit(DQb + ((size_t)(b * 8 + hp) * L + qb * 256) * 64, DKb + (size_t)(b * 8 + hp) * LT * 64, DVb + (size_t)(b * 4 + (hp >> 1)) * LT * 128,
;                            ODb + ((size_t)(b * 8 + hp) * L + qb * 256) * 128, LT, (char*)lds_raw);
;         }
.LBB0_526:
	s_cmp_lt_i32 s74, 4
	s_cselect_b64 s[0:1], -1, 0
	s_and_b64 s[8:9], s[0:1], s[4:5]
	s_andn2_b64 vcc, exec, s[8:9]
	s_cbranch_vccnz .LBB0_544
	s_cmpk_gt_i32 s2, 0x1ff
	s_cbranch_scc1 .LBB0_534
	s_add_u32 s3, s30, 0xa700000
	s_addc_u32 s14, s31, 0
	s_add_u32 s15, s30, 0xb700000
	s_addc_u32 s16, s31, 0
	s_add_u32 s17, s30, 0xc900000
	s_addc_u32 s19, s31, 0
	v_mov_b32_e32 v138, 0
	s_movk_i32 s22, 0x70
	s_movk_i32 s23, 0x2000
	s_movk_i32 s34, 0x4000
	s_movk_i32 s35, 0x6000
	v_mov_b32_e32 v1, 0x48000
	v_mov_b32_e32 v152, 0x90000
	s_mov_b32 s40, 0xc908000
	s_mov_b32 s41, 0xc90a000
	s_mov_b32 s42, 0xb704000
	s_mov_b32 s43, 0xc90c000
	s_mov_b32 s46, 0xc90e000
	s_mov_b32 s47, 0xb706000
	s_add_u32 s80, s30, 0xc908000
	s_addc_u32 s81, s31, 0
	s_add_u32 s82, s30, 0xc90a000
	s_addc_u32 s83, s31, 0
	s_add_u32 s84, s30, 0xb704000
	s_addc_u32 s85, s31, 0
	s_add_u32 s86, s30, 0xc90c000
	s_addc_u32 s87, s31, 0
	s_add_u32 s88, s30, 0xc90e000
	s_addc_u32 s89, s31, 0
	s_add_u32 s90, s30, 0xb706000
	s_addc_u32 s91, s31, 0
	s_mov_b64 s[0:1], 0x4000
	s_mov_b64 s[4:5], 0x8000
	s_movk_i32 s48, 0x7fff
	s_mov_b32 s49, s2
	s_mov_b32 s50, s2
	s_branch .LBB0_530

; __device__ __forceinline__ float log2_sigmoid(float x) { return -log1pf(expf(-x)) * 1.4426950408889634f; }
; __global__ void __launch_bounds__(NTHR, 2) mega(Args args) {
;     ...
;     if (IN(4)) { for (int rep = 0; rep < (MK_DUP == 4 ? 2 : 1); ++rep) {
;         __syncthreads();
;         const float* decay = args.in[9]; const float* ret_g = args.in[10]; const float* lamp = args.in[12]; const float* diff_g = args.in[13];
;         bf16* MIX = (bf16*)(ws + WS_MIX);
;         for (int idx = blockIdx.x; idx < 256; idx += G) {
;             const int b = idx & 7, rest = idx >> 3, h = rest >> 3, blk = rest & 7, c = blk + 1;
;             ret::out_unit((const bf16*)(ws + WS_RQ) + ((size_t)(b * 4 + h) * L + 256 * blk) * 64, (const bf16*)(ws + WS_RK) + ((size_t)(b * 4 + h) * LT + 256 * c) * 64,
;                           (const bf16*)(ws + WS_RV) + ((size_t)(b * 4 + h) * LT + 256 * c) * 128, (const float*)(ws + WS_ST) + (size_t)(b * 4 + h) * 9 * 2 * 8192, c,
;                           (const bf16*)(ws + WS_RG) + ((size_t)b * L + 256 * blk) * 512 + h * 128, ret_g + h * 128, MIX + ((size_t)b * L + 256 * blk) * D + h * 128,
;                           ret::log2_sigmoid(decay[h]), ret::log2_sigmoid(decay[4 + h]), (char*)lds_raw);
;         }
.LBB0_598:
	s_cmp_lt_i32 s74, 5
	s_cselect_b64 s[4:5], -1, 0
	s_and_b64 s[0:1], s[4:5], s[0:1]
	s_andn2_b64 vcc, exec, s[0:1]
	s_cbranch_vccnz .LBB0_643
	s_add_u32 s22, s30, 0xa700000
	s_addc_u32 s23, s31, 0
	s_mov_b32 s87, s77
	s_cmpk_gt_i32 s2, 0xff
	s_cbranch_scc1 .LBB0_634
	s_add_u32 s3, s30, 0x7400000
	s_addc_u32 s19, s31, 0
	s_add_u32 s34, s30, 0x7c00000
	s_addc_u32 s35, s31, 0
	s_add_u32 s47, s30, 0x8500000
	s_addc_u32 s49, s31, 0
	s_add_u32 s66, s30, 0xdb00000
	s_addc_u32 s67, s31, 0
	s_add_u32 s68, s30, 0x9700000
	s_addc_u32 s69, s31, 0
	s_mov_b32 s25, 0
	v_mov_b32_e32 v117, 0
	s_mov_b32 s42, 0xbfb8aa3b
	s_mov_b32 s43, 0x42ce8ed0
	s_mov_b32 s70, 0xc2b17218
	s_mov_b32 s71, 0x7f800000
	v_mov_b32_e32 v1, 0x7f800000
	s_mov_b32 s72, 0x3f2aaaab
	v_mov_b32_e32 v127, 0x3ecc95a3
	s_mov_b32 s73, 0x3f317218
	s_mov_b32 s76, 0x33800000
	s_movk_i32 s77, 0x4000
	s_movk_i32 s79, 0x6000
	s_add_i32 s80, 0, 0x14000
	s_mov_b64 s[40:41], 0x8000
	s_movk_i32 s81, 0x7fff
	s_mov_b32 s82, 0xffff0000
	s_brev_b32 s46, 60
	s_mov_b32 s48, 0x358637bd
	s_mov_b32 s74, 0x800000
	s_mov_b32 s75, s2

;     __device__ __forceinline__ bool next(int i, pg8::Unit& u) const { if (i > 0) return false; u.pm = pm; u.pn = pn; return true; }
;     __host__ __device__ bool next(int i, Unit& u) const {
;         const long L = (long)i * G + c; if (L >= nwg) return false;
;         int wgid = (int)L; { const int q = nwg / NXCD, r = nwg % NXCD, xcd = wgid % NXCD, off = wgid / NXCD; wgid = (xcd < r ? xcd * (q + 1) : r * (q + 1) + (xcd - r) * q) + off; }
;         const int nig = WGM * nN, gid = wgid / nig, fm = gid * WGM, gsz = (nM - fm) < WGM ? (nM - fm) : WGM;
;         u.pm = fm + ((wgid % nig) % gsz); u.pn = (wgid % nig) / gsz; return true;
; __global__ void __launch_bounds__(NTHR, 2) mega(Args args) {
;     ...
;     if (IN(5)) { for (int rep = 0; rep < (MK_DUP == 5 ? 2 : 1); ++rep) {
;         __syncthreads();
;         pg8::Gemm g{(const bf16*)(ws + WS_MIX), WoutT, M2, D, D}; pg8::StaticOrder S; S.init(M2, D, G, (int)blockIdx.x);
;         EpiOutProj E{x, (bf16*)(ws + WS_X1B), (bf16*)(ws + WS_X1A), mod, alpha2, (float*)(ws + WS_SSQ)};
;         pg8::gemm_phase<EpiOutProj, pg8::StaticOrder, PG8_ALIGN, PG8_SP2>(lds, g, S, E);
.LBB0_697:
	s_cmp_lt_i32 s74, 6
	s_cselect_b64 s[0:1], -1, 0
	s_and_b64 s[0:1], s[0:1], s[4:5]
	s_andn2_b64 vcc, exec, s[0:1]
	s_cbranch_vccnz .LBB0_736
	s_cmpk_lt_i32 s2, 0x100
	v_mov_b32_e32 v10, v0
	s_cselect_b64 s[4:5], -1, 0
	s_cmpk_gt_i32 s2, 0xff
	s_nop 0
	v_readfirstlane_b32 s6, v10
	s_cbranch_scc1 .LBB0_700
	s_ashr_i32 s3, s2, 31
	s_lshr_b32 s3, s3, 29
	s_add_i32 s3, s2, s3
	s_ashr_i32 s7, s3, 3
	s_and_b32 s3, s3, -8
	s_sub_i32 s3, s2, s3
	s_lshl_b32 s9, s3, 5
	s_mul_i32 s8, s3, 33
	s_cmp_lt_i32 s3, 0
	s_cselect_b32 s3, s8, s9
	s_add_i32 s3, s3, s7
	s_ashr_i32 s7, s3, 31
	s_lshr_b32 s7, s7, 27
	s_add_i32 s7, s3, s7
	s_ashr_i32 s8, s7, 5
	s_and_b32 s7, s7, 0xffe0
	s_sub_i32 s3, s3, s7
	s_bfe_i32 s7, s3, 0x80000
	s_bfe_u32 s7, s7, 0x3000c
	s_add_i32 s7, s3, s7
	s_bfe_i32 s9, s7, 0x80000
	s_and_b32 s7, s7, 0xf8
	s_sub_i32 s3, s3, s7
	s_lshl_b32 s8, s8, 3
	s_sext_i32_i16 s9, s9
	s_sext_i32_i8 s3, s3
	s_add_i32 s60, s8, s3
	s_ashr_i32 s8, s9, 3

; #define LAS __attribute__((address_space(3)))
; __device__ __forceinline__ void gatherA_fused(int tok0, int cstart, const unsigned char* __restrict__ HQ, const float* __restrict__ HS, const int* __restrict__ pidx, const float* __restrict__ pgate, unsigned char* __restrict__ recs  , ...
;     int tid = threadIdx.x; asm volatile("" : "+v"(tid));
;     const int wid = tid >> 6, lane = tid & 63, r = lane >> 3, s = lane & 7;
;     const int tw0 = tok0 + wid * 8;
;     const unsigned loff = 16u * (unsigned)s, l4 = 4u * (unsigned)lane;
;     const unsigned char* pib = (const unsigned char*)pidx;
;     LAS unsigned char* ring = (LAS unsigned char*)lds + wid * 16384;
;     LAS unsigned char* meta = (LAS unsigned char*)lds + 132096 + wid * 1552;
; __global__ void __launch_bounds__(NTHR, 2) mega(Args args) {
;     ...
;     if (IN(8)) { for (int rep = 0; rep < (MK_DUP == 8 ? 2 : 1); ++rep) {
;         __syncthreads();
;         for (int grp = blockIdx.x; grp < M2 / 64; grp += G) {
;             peer::gatherA_fused(grp * 64, (int)blockIdx.x & 3, ws + WS_HQ, (const float*)(ws + WS_HS), (const int*)(ws + WS_PIDX), (const float*)(ws + WS_PGATE), ws + WS_PW2, UT8, SUs, SVs, (char*)lds_raw);
;             __syncthreads();
;             peer::gatherB_fused(grp * 64, (int)blockIdx.x & 3, args.out, (const bf16*)(ws + WS_X1B), mod, (const unsigned*)(ws + WS_PW2), VT8, (char*)lds_raw);
;             __syncthreads(); }
.LBB0_868:
	s_cmp_lt_i32 s74, 9
	s_cselect_b64 s[0:1], -1, 0
	s_cmp_gt_i32 s75, 8
	s_cselect_b64 s[4:5], -1, 0
	s_and_b64 s[0:1], s[0:1], s[4:5]
	s_andn2_b64 vcc, exec, s[0:1]
	s_cbranch_vccnz .LBB0_1057
	s_cmpk_gt_i32 s2, 0xff
	s_cbranch_scc1 .LBB0_1057
	s_add_u32 s3, s30, 0x1000000
	s_addc_u32 s19, s31, 0
	s_and_b32 s33, s2, 3
	s_add_u32 s10, s30, 0xb400000
	s_addc_u32 s11, s31, 0
	s_add_u32 s12, s30, 0xc400000
	s_addc_u32 s13, s31, 0
	s_add_u32 s14, s30, 0xc800000
	s_addc_u32 s15, s31, 0
	s_add_u32 s16, s30, 0xd000000
	s_addc_u32 s17, s31, 0
	s_add_u32 s22, s30, 0x3400000
	s_addc_u32 s23, s31, 0
	s_lshl_b32 s58, s33, 14
	s_lshl_b32 s0, s33, 21
	s_add_u32 s34, s3, s0
	s_addc_u32 s35, s19, 0
	s_lshl_b32 s1, s33, 22
	s_add_u32 s36, s10, s1
	s_addc_u32 s37, s11, 0
	s_lshl_b32 s1, s33, 16
	s_add_u32 s40, s12, s1
	s_addc_u32 s41, s13, 0
	s_add_u32 s42, s30, 0x8500000
	s_addc_u32 s43, s31, 0
	s_add_u32 s44, s20, s0
	s_addc_u32 s45, s21, 0
	s_lshl_b32 s0, s2, 9
	s_addk_i32 s0, 0x600
	s_and_b32 s0, s0, 0x600
	s_add_u32 s46, s42, s0
	s_addc_u32 s47, s43, 0
	s_lshl_b32 s0, s2, 8
	s_addk_i32 s0, 0x300
	s_and_b32 s60, s0, 0x300
	s_add_u32 s48, s30, 0x3000000
	s_addc_u32 s49, s31, 0
	s_add_u32 s61, s30, 0x105000
	v_mbcnt_lo_u32_b32 v2, -1, 0
	s_mov_b32 s25, 0
	s_movk_i32 s59, 0x300
	s_addc_u32 s62, s31, 0
	s_movk_i32 s63, 0x610
	s_add_i32 s64, 0, 0x20400
	s_movk_i32 s65, 0x400
	v_mov_b32_e32 v91, 0
	s_mov_b32 s66, 0x378e98ab
	s_mov_b32 s67, 0x3b7cd369
	s_mov_b32 s68, 0xbcc618b2
	s_mov_b32 s69, 0x3dda74e4
	s_mov_b32 s70, 0x3f228afd
	s_mov_b32 s71, 0x3e03c728
	s_mov_b32 s72, 0xbfb8aa3b
	s_mov_b32 s73, 0x42ce8ed0
	s_mov_b32 s74, 0xc2b17218
	v_mov_b32_e32 v1, 0x3ba10414
	s_brev_b32 s75, -2
	s_movk_i32 s76, 0xff9c
	s_movk_i32 s77, 0x1ff
	s_add_i32 s78, 0, 0x22400
	s_mov_b64 s[30:31], 0x800
	s_movk_i32 s79, 0x70
	s_movk_i32 s80, 0x50
	s_movk_i32 s81, 0x60
	s_movk_i32 s82, 0xc0
	s_mov_b32 s83, 0x1fff80
	s_add_i32 s84, 0, 0x21400
	v_mov_b32_e32 v102, 0xb9c68948
	v_mov_b32_e32 v103, 0x7f800000
	v_mbcnt_hi_u32_b32 v104, -1, v2
	v_mov_b32_e32 v105, 0x64
	v_mov_b32_e32 v106, 0x70
	v_mov_b32_e32 v107, 0x100
	v_mov_b32_e32 v108, 0x180
	s_branch .LBB0_873
